# adds pipelined gla_combine loops, XCD-local scan unit mapping and 3-deep prefix-state loop
# speedup vs baseline: 1.0215x; 1.0077x over previous
.LBB0_297:
	s_and_b64 s[34:35], s[26:27], exec
	s_cselect_b32 s34, s29, s33
	s_lshl_b32 s34, s34, 1
	s_or_b32 s34, s34, s2
	s_ashr_i32 s35, s34, 31
	s_lshl_b64 s[36:37], s[34:35], 17
	s_lshl_b64 s[34:35], s[34:35], 9
	v_lshl_add_u64 v[18:19], v[16:17], 0, s[36:37]
	v_lshl_add_u64 v[20:21], v[42:43], 0, s[34:35]
	v_lshl_add_u64 v[48:49], v[18:19], 0, v[34:35]
	v_lshl_add_u64 v[50:51], v[18:19], 0, v[36:37]
	v_lshl_add_u64 v[52:53], v[18:19], 0, v[38:39]
	global_load_dword v22, v[20:21], off sc0 sc1
	v_lshl_add_u64 v[18:19], v[18:19], 0, v[40:41]
	global_load_dword v132, v[48:49], off sc0 sc1
	global_load_dword v134, v[48:49], off offset:64 sc0 sc1
	global_load_dword v136, v[48:49], off offset:128 sc0 sc1
	s_nop 0
	global_load_dword v48, v[48:49], off offset:192 sc0 sc1
	s_nop 0
	global_load_dword v23, v[20:21], off offset:4 sc0 sc1
	global_load_dword v133, v[50:51], off sc0 sc1
	global_load_dword v135, v[50:51], off offset:64 sc0 sc1
	global_load_dword v137, v[50:51], off offset:128 sc0 sc1
	global_load_dword v49, v[50:51], off offset:192 sc0 sc1
	s_nop 0
	global_load_dword v50, v[20:21], off offset:8 sc0 sc1
	global_load_dword v138, v[52:53], off sc0 sc1
	global_load_dword v140, v[52:53], off offset:64 sc0 sc1
	global_load_dword v142, v[52:53], off offset:128 sc0 sc1
	s_nop 0
	global_load_dword v52, v[52:53], off offset:192 sc0 sc1
	s_nop 0
	global_load_dword v51, v[20:21], off offset:12 sc0 sc1
	global_load_dword v139, v[18:19], off sc0 sc1
	global_load_dword v141, v[18:19], off offset:64 sc0 sc1
	global_load_dword v143, v[18:19], off offset:128 sc0 sc1
	global_load_dword v53, v[18:19], off offset:192 sc0 sc1
	s_add_i32 s33, s33, -1
	s_add_i32 s29, s29, 1
	s_cmp_lt_u32 s30, 2
	s_cbranch_scc1 .Lpf_w1
	s_and_b64 s[34:35], s[26:27], exec
	s_cselect_b32 s34, s29, s33
	s_lshl_b32 s34, s34, 1
	s_or_b32 s34, s34, s2
	s_ashr_i32 s35, s34, 31
	s_lshl_b64 s[36:37], s[34:35], 17
	s_lshl_b64 s[34:35], s[34:35], 9
	v_lshl_add_u64 v[160:161], v[16:17], 0, s[36:37]
	v_lshl_add_u64 v[162:163], v[42:43], 0, s[34:35]
	v_lshl_add_u64 v[166:167], v[160:161], 0, v[34:35]
	v_lshl_add_u64 v[168:169], v[160:161], 0, v[36:37]
	v_lshl_add_u64 v[170:171], v[160:161], 0, v[38:39]
	global_load_dword v164, v[162:163], off sc0 sc1
	v_lshl_add_u64 v[160:161], v[160:161], 0, v[40:41]
	global_load_dword v172, v[166:167], off sc0 sc1
	global_load_dword v174, v[166:167], off offset:64 sc0 sc1
	global_load_dword v182, v[166:167], off offset:128 sc0 sc1
	s_nop 0
	global_load_dword v166, v[166:167], off offset:192 sc0 sc1
	s_nop 0
	global_load_dword v165, v[162:163], off offset:4 sc0 sc1
	global_load_dword v173, v[168:169], off sc0 sc1
	global_load_dword v175, v[168:169], off offset:64 sc0 sc1
	global_load_dword v183, v[168:169], off offset:128 sc0 sc1
	global_load_dword v167, v[168:169], off offset:192 sc0 sc1
	s_nop 0
	global_load_dword v168, v[162:163], off offset:8 sc0 sc1
	global_load_dword v184, v[170:171], off sc0 sc1
	global_load_dword v186, v[170:171], off offset:64 sc0 sc1
	global_load_dword v188, v[170:171], off offset:128 sc0 sc1
	s_nop 0
	global_load_dword v170, v[170:171], off offset:192 sc0 sc1
	s_nop 0
	global_load_dword v169, v[162:163], off offset:12 sc0 sc1
	global_load_dword v185, v[160:161], off sc0 sc1
	global_load_dword v187, v[160:161], off offset:64 sc0 sc1
	global_load_dword v189, v[160:161], off offset:128 sc0 sc1
	global_load_dword v171, v[160:161], off offset:192 sc0 sc1
	s_add_i32 s33, s33, -1
	s_add_i32 s29, s29, 1
	s_cmp_lt_u32 s30, 3
	s_cbranch_scc1 .Lpf_w2
	s_and_b64 s[34:35], s[26:27], exec
	s_cselect_b32 s34, s29, s33
	s_lshl_b32 s34, s34, 1
	s_or_b32 s34, s34, s2
	s_ashr_i32 s35, s34, 31
	s_lshl_b64 s[36:37], s[34:35], 17
	s_lshl_b64 s[34:35], s[34:35], 9
	v_lshl_add_u64 v[190:191], v[16:17], 0, s[36:37]
	v_lshl_add_u64 v[192:193], v[42:43], 0, s[34:35]
	v_lshl_add_u64 v[196:197], v[190:191], 0, v[34:35]
	v_lshl_add_u64 v[198:199], v[190:191], 0, v[36:37]
	v_lshl_add_u64 v[200:201], v[190:191], 0, v[38:39]
	global_load_dword v194, v[192:193], off sc0 sc1
	v_lshl_add_u64 v[190:191], v[190:191], 0, v[40:41]
	global_load_dword v214, v[196:197], off sc0 sc1
	global_load_dword v216, v[196:197], off offset:64 sc0 sc1
	global_load_dword v218, v[196:197], off offset:128 sc0 sc1
	s_nop 0
	global_load_dword v196, v[196:197], off offset:192 sc0 sc1
	s_nop 0
	global_load_dword v195, v[192:193], off offset:4 sc0 sc1
	global_load_dword v215, v[198:199], off sc0 sc1
	global_load_dword v217, v[198:199], off offset:64 sc0 sc1
	global_load_dword v219, v[198:199], off offset:128 sc0 sc1
	global_load_dword v197, v[198:199], off offset:192 sc0 sc1
	s_nop 0
	global_load_dword v198, v[192:193], off offset:8 sc0 sc1
	global_load_dword v220, v[200:201], off sc0 sc1
	global_load_dword v222, v[200:201], off offset:64 sc0 sc1
	global_load_dword v224, v[200:201], off offset:128 sc0 sc1
	s_nop 0
	global_load_dword v200, v[200:201], off offset:192 sc0 sc1
	s_nop 0
	global_load_dword v199, v[192:193], off offset:12 sc0 sc1
	global_load_dword v221, v[190:191], off sc0 sc1
	global_load_dword v223, v[190:191], off offset:64 sc0 sc1
	global_load_dword v225, v[190:191], off offset:128 sc0 sc1
	global_load_dword v201, v[190:191], off offset:192 sc0 sc1
	s_add_i32 s33, s33, -1
	s_add_i32 s29, s29, 1
	s_waitcnt vmcnt(40)
	v_pk_fma_f32 v[2:3], v[2:3], v[50:51], v[138:139]
	v_pk_fma_f32 v[12:13], v[12:13], v[22:23], v[48:49]
	v_pk_fma_f32 v[10:11], v[10:11], v[50:51], v[142:143]
	v_pk_fma_f32 v[14:15], v[14:15], v[50:51], v[52:53]
	v_pk_fma_f32 v[8:9], v[8:9], v[22:23], v[136:137]
	v_pk_fma_f32 v[6:7], v[6:7], v[50:51], v[140:141]
	v_pk_fma_f32 v[4:5], v[4:5], v[22:23], v[134:135]
	v_pk_fma_f32 v[0:1], v[0:1], v[22:23], v[132:133]
	s_waitcnt vmcnt(20)
	v_pk_fma_f32 v[2:3], v[2:3], v[168:169], v[184:185]
	v_pk_fma_f32 v[12:13], v[12:13], v[164:165], v[166:167]
	v_pk_fma_f32 v[10:11], v[10:11], v[168:169], v[188:189]
	v_pk_fma_f32 v[14:15], v[14:15], v[168:169], v[170:171]
	v_pk_fma_f32 v[8:9], v[8:9], v[164:165], v[182:183]
	v_pk_fma_f32 v[6:7], v[6:7], v[168:169], v[186:187]
	v_pk_fma_f32 v[4:5], v[4:5], v[164:165], v[174:175]
	v_pk_fma_f32 v[0:1], v[0:1], v[164:165], v[172:173]
	s_waitcnt vmcnt(0)
	v_pk_fma_f32 v[2:3], v[2:3], v[198:199], v[220:221]
	v_pk_fma_f32 v[12:13], v[12:13], v[194:195], v[196:197]
	v_pk_fma_f32 v[10:11], v[10:11], v[198:199], v[224:225]
	v_pk_fma_f32 v[14:15], v[14:15], v[198:199], v[200:201]
	v_pk_fma_f32 v[8:9], v[8:9], v[194:195], v[218:219]
	v_pk_fma_f32 v[6:7], v[6:7], v[198:199], v[222:223]
	v_pk_fma_f32 v[4:5], v[4:5], v[194:195], v[216:217]
	v_pk_fma_f32 v[0:1], v[0:1], v[194:195], v[214:215]
	s_add_i32 s30, s30, -3
	s_cmp_eq_u32 s30, 0
	s_cbranch_scc0 .LBB0_297
	s_branch .LBB0_299
.Lpf_w2:
	s_waitcnt vmcnt(20)
	v_pk_fma_f32 v[2:3], v[2:3], v[50:51], v[138:139]
	v_pk_fma_f32 v[12:13], v[12:13], v[22:23], v[48:49]
	v_pk_fma_f32 v[10:11], v[10:11], v[50:51], v[142:143]
	v_pk_fma_f32 v[14:15], v[14:15], v[50:51], v[52:53]
	v_pk_fma_f32 v[8:9], v[8:9], v[22:23], v[136:137]
	v_pk_fma_f32 v[6:7], v[6:7], v[50:51], v[140:141]
	v_pk_fma_f32 v[4:5], v[4:5], v[22:23], v[134:135]
	v_pk_fma_f32 v[0:1], v[0:1], v[22:23], v[132:133]
	s_waitcnt vmcnt(0)
	v_pk_fma_f32 v[2:3], v[2:3], v[168:169], v[184:185]
	v_pk_fma_f32 v[12:13], v[12:13], v[164:165], v[166:167]
	v_pk_fma_f32 v[10:11], v[10:11], v[168:169], v[188:189]
	v_pk_fma_f32 v[14:15], v[14:15], v[168:169], v[170:171]
	v_pk_fma_f32 v[8:9], v[8:9], v[164:165], v[182:183]
	v_pk_fma_f32 v[6:7], v[6:7], v[168:169], v[186:187]
	v_pk_fma_f32 v[4:5], v[4:5], v[164:165], v[174:175]
	v_pk_fma_f32 v[0:1], v[0:1], v[164:165], v[172:173]
	s_branch .LBB0_299
.Lpf_w1:
	s_waitcnt vmcnt(0)
	v_pk_fma_f32 v[2:3], v[2:3], v[50:51], v[138:139]
	v_pk_fma_f32 v[12:13], v[12:13], v[22:23], v[48:49]
	v_pk_fma_f32 v[10:11], v[10:11], v[50:51], v[142:143]
	v_pk_fma_f32 v[14:15], v[14:15], v[50:51], v[52:53]
	v_pk_fma_f32 v[8:9], v[8:9], v[22:23], v[136:137]
	v_pk_fma_f32 v[6:7], v[6:7], v[50:51], v[140:141]
	v_pk_fma_f32 v[4:5], v[4:5], v[22:23], v[134:135]
	v_pk_fma_f32 v[0:1], v[0:1], v[22:23], v[132:133]
	s_branch .LBB0_299

.LBB0_309:
	s_and_b32 s98, s18, 7
	s_lshr_b32 s99, s18, 3
	s_lshl_b32 s98, s98, 5
	s_add_i32 s98, s98, s99
	s_ashr_i32 s20, s98, 3
	s_and_b32 s19, s98, 3
	s_bfe_u32 s21, s98, 0x10002
	s_cmp_eq_u32 s21, 0
	s_cselect_b64 s[14:15], -1, 0
	s_lshl_b32 s94, s21, 9
	v_lshl_add_u64 v[38:39], v[20:21], 0, s[94:95]
	s_lshl_b32 s94, s19, 7
	v_mov_b32_e32 v96, 0
	s_mov_b32 s23, 0
	s_lshl_b32 s24, s20, 10
	s_lshl_b32 s22, s19, 6
	v_cndmask_b32_e64 v37, v25, v42, s[14:15]
	v_cndmask_b32_e64 v97, v48, v47, s[14:15]
	v_cndmask_b32_e64 v98, v50, v49, s[14:15]
	v_cndmask_b32_e64 v99, v52, v51, s[14:15]
	v_cndmask_b32_e64 v100, v54, v53, s[14:15]
	v_cndmask_b32_e64 v101, v56, v55, s[14:15]
	v_cndmask_b32_e64 v102, v58, v57, s[14:15]
	v_cndmask_b32_e64 v103, v60, v59, s[14:15]
	v_cndmask_b32_e64 v104, v62, v61, s[14:15]
	v_cndmask_b32_e64 v105, v64, v63, s[14:15]
	v_cndmask_b32_e64 v106, v66, v65, s[14:15]
	v_cndmask_b32_e64 v107, v68, v67, s[14:15]
	v_cndmask_b32_e64 v108, v70, v69, s[14:15]
	v_cndmask_b32_e64 v109, v72, v71, s[14:15]
	v_cndmask_b32_e64 v110, v74, v73, s[14:15]
	v_cndmask_b32_e64 v111, v76, v75, s[14:15]
	v_cndmask_b32_e64 v112, v77, v43, s[14:15]
	v_cndmask_b32_e64 v113, v79, v78, s[14:15]
	v_cndmask_b32_e64 v114, v81, v80, s[14:15]
	v_cndmask_b32_e64 v115, v83, v82, s[14:15]
	v_cndmask_b32_e64 v116, v85, v84, s[14:15]
	s_movk_i32 s25, 0x3c0
	v_mov_b32_e32 v0, 0
	v_mov_b32_e32 v1, v96
	v_mov_b32_e32 v2, v96
	v_mov_b32_e32 v3, v96
	v_mov_b32_e32 v4, 0
	v_mov_b32_e32 v5, v96
	v_mov_b32_e32 v6, v96
	v_mov_b32_e32 v7, v96
	v_mov_b32_e32 v8, 0
	v_mov_b32_e32 v9, v96
	v_mov_b32_e32 v10, v96
	v_mov_b32_e32 v11, v96
	v_mov_b32_e32 v12, 0
	v_mov_b32_e32 v13, v96
	v_mov_b32_e32 v14, v96
	v_mov_b32_e32 v15, v96
	v_cndmask_b32_e64 v117, v87, v86, s[14:15]
	v_cndmask_b32_e64 v118, v89, v88, s[14:15]
	v_cndmask_b32_e64 v119, v91, v90, s[14:15]
	v_lshl_add_u64 v[40:41], v[22:23], 0, s[94:95]
	s_mov_b32 s26, 0xc988000
	s_and_b64 s[2:3], s[14:15], exec
	s_cselect_b32 s2, s23, s25
	s_add_i32 s2, s2, s24
	v_add_u32_e32 v246, s2, v37
	v_mov_b32_e32 v245, 0
	v_add_u32_e32 v247, s2, v112
	v_lshl_add_u64 v[240:241], s[46:47], 0, v[176:177]
	v_add_co_u32_e64 v240, s[16:17], s26, v240
	s_nop 1
	v_addc_co_u32_e64 v241, s[16:17], 0, v241, s[16:17]
	s_cmp_lg_u64 s[14:15], 0
	s_cbranch_scc0 .Lsa_bwd_pre
	v_add_u32_e32 v244, 4, v246
	v_lshlrev_b32_e32 v244, 10, v244
	v_lshl_add_u64 v[236:237], v[244:245], 0, v[38:39]
	v_add_u32_e32 v244, 12, v246
	v_lshlrev_b32_e32 v244, 10, v244
	v_lshl_add_u64 v[238:239], v[244:245], 0, v[38:39]
	v_add_u32_e32 v244, 8, v246
	v_lshlrev_b32_e32 v244, 9, v244
	v_lshl_add_u64 v[240:241], v[244:245], 0, v[240:241]
	v_lshlrev_b32_e32 v244, 9, v247
	v_lshl_add_u64 v[242:243], v[244:245], 0, v[40:41]
	global_load_dword v159, v[236:237], off offset:-4096 sc0 sc1
	global_load_ushort v160, v[240:241], off offset:-3840 sc0 sc1
	global_load_dword v161, v[236:237], off offset:-3072 sc0 sc1
	global_load_ushort v162, v[240:241], off offset:-3328 sc0 sc1
	global_load_dword v163, v[236:237], off offset:-2048 sc0 sc1
	global_load_ushort v164, v[240:241], off offset:-2816 sc0 sc1
	global_load_dword v165, v[236:237], off offset:-1024 sc0 sc1
	global_load_ushort v166, v[240:241], off offset:-2304 sc0 sc1
	global_load_dword v167, v[236:237], off sc0 sc1
	global_load_ushort v168, v[240:241], off offset:-1792 sc0 sc1
	global_load_dword v169, v[236:237], off offset:1024 sc0 sc1
	global_load_ushort v170, v[240:241], off offset:-1280 sc0 sc1
	global_load_dword v171, v[236:237], off offset:2048 sc0 sc1
	global_load_ushort v172, v[240:241], off offset:-768 sc0 sc1
	global_load_dword v173, v[236:237], off offset:3072 sc0 sc1
	global_load_ushort v174, v[240:241], off offset:-256 sc0 sc1
	global_load_dword v175, v[238:239], off offset:-4096 sc0 sc1
	global_load_ushort v182, v[240:241], off offset:256 sc0 sc1
	global_load_dword v183, v[238:239], off offset:-3072 sc0 sc1
	global_load_ushort v184, v[240:241], off offset:768 sc0 sc1
	global_load_dword v185, v[238:239], off offset:-2048 sc0 sc1
	global_load_ushort v186, v[240:241], off offset:1280 sc0 sc1
	global_load_dword v187, v[238:239], off offset:-1024 sc0 sc1
	global_load_ushort v188, v[240:241], off offset:1792 sc0 sc1
	global_load_dword v189, v[238:239], off sc0 sc1
	global_load_ushort v190, v[240:241], off offset:2304 sc0 sc1
	global_load_dword v191, v[238:239], off offset:1024 sc0 sc1
	global_load_ushort v192, v[240:241], off offset:2816 sc0 sc1
	global_load_dword v193, v[238:239], off offset:2048 sc0 sc1
	global_load_ushort v194, v[240:241], off offset:3328 sc0 sc1
	global_load_dword v195, v[238:239], off offset:3072 sc0 sc1
	global_load_ushort v196, v[240:241], off offset:3840 sc0 sc1
	global_load_ushort v197, v[242:243], off sc0 sc1
	global_load_ushort v198, v[242:243], off offset:512 sc0 sc1
	global_load_ushort v199, v[242:243], off offset:1024 sc0 sc1
	global_load_ushort v200, v[242:243], off offset:1536 sc0 sc1
	global_load_ushort v201, v[242:243], off offset:2048 sc0 sc1
	global_load_ushort v213, v[242:243], off offset:2560 sc0 sc1
	global_load_ushort v214, v[242:243], off offset:3072 sc0 sc1
	global_load_ushort v215, v[242:243], off offset:3584 sc0 sc1
	s_branch .Lsa_done_pre
